# L3 conv-branch-A loop: loop-invariant conv weights hoisted to the preheader, a_b load issued with a_x/a_c loads
# speedup vs baseline: 1.0773x; 1.0048x over previous
.LBB0_725:
	s_or_b64 exec, exec, s[4:5]
	s_mov_b64 s[4:5], s[0:1]
	s_waitcnt lgkmcnt(0)
	s_barrier
	s_load_dwordx2 s[12:13], s[4:5], 0x108
	v_mov_b32_e32 v45, v205
	s_mov_b64 s[10:11], s[0:1]
	s_mov_b64 s[8:9], s[0:1]
	v_readlane_b32 s6, v252, 42
	s_mov_b32 s14, s61
	s_waitcnt lgkmcnt(0)
	s_add_u32 s4, s12, 0x26a0000
	s_mul_i32 s2, s6, 0x600
	s_mov_b32 s6, 0x140000
	v_lshl_add_u32 v30, s14, 8, v45
	s_addc_u32 s5, s13, 0
	v_readlane_b32 s7, v252, 43
	v_cmp_gt_i32_e32 vcc, s6, v30
	s_and_saveexec_b64 s[6:7], vcc
	s_cbranch_execz .LBB0_732
	s_load_dwordx2 s[10:11], s[10:11], 0x108
	s_nop 0
	s_load_dwordx2 s[16:17], s[8:9], 0x48
	v_lshlrev_b32_e32 v0, 3, v45
	v_lshl_add_u32 v31, s14, 11, v0
	s_mov_b64 s[14:15], 0
	s_waitcnt lgkmcnt(0)
	s_add_u32 s8, s10, 0x14b20000
	s_addc_u32 s9, s11, 0
	s_lshl_b64 s[10:11], s[2:3], 2
	s_add_u32 s10, s16, s10
	s_addc_u32 s11, s17, s11
	v_and_b32_e32 v158, 0x1f8, v31
	v_lshlrev_b32_e32 v158, 2, v158
	v_add_u32_e32 v159, 0x1000, v158
	global_load_dwordx4 v[134:137], v158, s[10:11] offset:16
	global_load_dwordx4 v[138:141], v158, s[10:11]
	global_load_dwordx4 v[142:145], v158, s[10:11] offset:2064
	global_load_dwordx4 v[146:149], v158, s[10:11] offset:2048
	global_load_dwordx4 v[150:153], v159, s[10:11]
	global_load_dwordx4 v[154:157], v159, s[10:11] offset:16
	s_waitcnt vmcnt(0)
	s_branch .LBB0_728
.LBB0_727:
	s_or_b64 exec, exec, s[16:17]
	s_waitcnt vmcnt(2)
	v_lshlrev_b32_e32 v28, 16, v4
	v_and_b32_e32 v29, 0xffff0000, v4
	s_waitcnt vmcnt(1)
	v_lshlrev_b32_e32 v34, 16, v0
	v_and_b32_e32 v35, 0xffff0000, v0
	v_lshlrev_b32_e32 v4, 16, v5
	v_and_b32_e32 v5, 0xffff0000, v5
	v_lshlrev_b32_e32 v0, 16, v1
	v_and_b32_e32 v1, 0xffff0000, v1
	v_pk_mul_f32 v[50:51], v[4:5], v[0:1]
	v_lshlrev_b32_e32 v0, 16, v6
	v_and_b32_e32 v1, 0xffff0000, v6
	v_lshlrev_b32_e32 v4, 16, v2
	v_and_b32_e32 v5, 0xffff0000, v2
	v_pk_mul_f32 v[52:53], v[0:1], v[4:5]
	v_lshlrev_b32_e32 v0, 16, v7
	v_and_b32_e32 v1, 0xffff0000, v7
	v_lshlrev_b32_e32 v2, 16, v3
	v_and_b32_e32 v3, 0xffff0000, v3
	v_pk_mul_f32 v[54:55], v[0:1], v[2:3]
	v_pk_mul_f32 v[28:29], v[28:29], v[34:35]
	v_readlane_b32 s16, v252, 5
	v_ashrrev_i32_e32 v9, 31, v8
	s_waitcnt vmcnt(0)
	v_lshlrev_b32_e32 v56, 16, v130
	v_and_b32_e32 v57, 0xffff0000, v130
	v_lshlrev_b32_e32 v0, 16, v131
	v_pk_mul_f32 v[18:19], v[28:29], v[146:147]
	v_and_b32_e32 v1, 0xffff0000, v131
	v_pk_fma_f32 v[28:29], v[16:17], v[138:139], v[18:19]
	v_add_u32_e32 v30, s16, v30
	s_nop 0
	s_nop 0
	v_readlane_b32 s16, v252, 23
	v_pk_fma_f32 v[10:11], v[10:11], v[150:151], v[28:29]
	v_pk_mul_f32 v[16:17], v[50:51], v[148:149]
	v_add_u32_e32 v31, s16, v31
	v_pk_fma_f32 v[12:13], v[12:13], v[140:141], v[16:17]
	v_pk_mul_f32 v[16:17], v[52:53], v[142:143]
	v_pk_fma_f32 v[12:13], v[22:23], v[152:153], v[12:13]
	v_pk_fma_f32 v[4:5], v[14:15], v[134:135], v[16:17]
	v_pk_mul_f32 v[12:13], v[12:13], v[0:1]
	v_lshlrev_b32_e32 v0, 16, v132
	v_and_b32_e32 v1, 0xffff0000, v132
	v_pk_fma_f32 v[4:5], v[24:25], v[154:155], v[4:5]
	s_mov_b32 s16, 0x13ffff
	v_pk_mul_f32 v[4:5], v[4:5], v[0:1]
	v_lshlrev_b32_e32 v0, 16, v133
	v_and_b32_e32 v1, 0xffff0000, v133
	v_pk_mul_f32 v[2:3], v[54:55], v[144:145]
	v_pk_mul_f32 v[10:11], v[10:11], v[56:57]
	v_pk_fma_f32 v[2:3], v[20:21], v[136:137], v[2:3]
	v_cmp_lt_i32_e32 vcc, s16, v30
	v_pk_fma_f32 v[2:3], v[26:27], v[156:157], v[2:3]
	s_or_b64 s[14:15], vcc, s[14:15]
	v_pk_mul_f32 v[6:7], v[2:3], v[0:1]
	v_cvt_pk_bf16_f32 v2, v4, v5
	v_lshlrev_b64 v[4:5], 10, v[8:9]
	v_lshl_add_u64 v[4:5], s[8:9], 0, v[4:5]
	v_cvt_pk_bf16_f32 v0, v10, v11
	v_cvt_pk_bf16_f32 v1, v12, v13
	v_cvt_pk_bf16_f32 v3, v6, v7
	v_lshl_add_u64 v[4:5], v[4:5], 0, v[128:129]
	global_store_dwordx4 v[4:5], v[0:3], off
	s_andn2_b64 exec, exec, s[14:15]
	s_cbranch_execz .LBB0_732
.LBB0_728:
	v_ashrrev_i32_e32 v8, 6, v30
	v_and_b32_e32 v32, 0x1f8, v31
	v_mov_b64_e32 v[0:1], s[4:5]
	v_mad_i64_i32 v[28:29], s[16:17], v8, s33, v[0:1]
	v_lshlrev_b32_e32 v128, 1, v32
	v_lshl_add_u64 v[18:19], v[28:29], 0, v[128:129]
	global_load_dwordx4 v[4:7], v[18:19], off
	global_load_dwordx4 v[0:3], v[18:19], off offset:2048
	global_load_dwordx4 v[130:133], v[18:19], off offset:1024
	v_cmp_lt_i32_e32 vcc, s82, v8
	v_mov_b32_e32 v10, 0
	v_mov_b32_e32 v20, 0
	v_cndmask_b32_e32 v9, v218, v219, vcc
	v_and_b32_e32 v11, v9, v8
	v_cmp_ne_u32_e32 vcc, 0, v11
	v_mov_b32_e32 v21, 0
	v_mov_b32_e32 v14, 0
	v_mov_b32_e32 v15, 0
	v_mov_b32_e32 v12, 0
	v_mov_b32_e32 v13, 0
	v_mov_b32_e32 v16, 0
	v_mov_b32_e32 v17, 0
	s_and_saveexec_b64 s[16:17], vcc
	s_cbranch_execz .LBB0_730
	v_add_co_u32_e32 v12, vcc, 0xffffe000, v18
	s_nop 1
	v_addc_co_u32_e32 v13, vcc, -1, v19, vcc
	global_load_dwordx4 v[20:23], v[12:13], off offset:-1152
	v_add_co_u32_e32 v12, vcc, 0xfffff000, v18
	s_nop 1
	v_addc_co_u32_e32 v13, vcc, -1, v19, vcc
	global_load_dwordx4 v[24:27], v[12:13], off offset:-3200
	s_waitcnt vmcnt(1)
	v_lshlrev_b32_e32 v12, 16, v20
	v_and_b32_e32 v13, 0xffff0000, v20
	s_waitcnt vmcnt(0)
	v_lshlrev_b32_e32 v14, 16, v24
	v_and_b32_e32 v15, 0xffff0000, v24
	v_pk_mul_f32 v[16:17], v[12:13], v[14:15]
	v_lshlrev_b32_e32 v12, 16, v21
	v_and_b32_e32 v13, 0xffff0000, v21
	v_lshlrev_b32_e32 v14, 16, v25
	v_and_b32_e32 v15, 0xffff0000, v25
	v_pk_mul_f32 v[12:13], v[12:13], v[14:15]
	v_lshlrev_b32_e32 v14, 16, v22
	v_and_b32_e32 v15, 0xffff0000, v22
	v_lshlrev_b32_e32 v20, 16, v26
	v_and_b32_e32 v21, 0xffff0000, v26
	v_pk_mul_f32 v[14:15], v[14:15], v[20:21]
	v_lshlrev_b32_e32 v20, 16, v23
	v_and_b32_e32 v21, 0xffff0000, v23
	v_lshlrev_b32_e32 v22, 16, v27
	v_and_b32_e32 v23, 0xffff0000, v27
	v_pk_mul_f32 v[20:21], v[20:21], v[22:23]
